# P4 y_prompt stores marked nt (streaming, never re-read)
# baseline (speedup 1.0000x reference)
.LBB0_699:
	s_or_b64 exec, exec, s[4:5]
	v_lshlrev_b64 v[128:129], 2, v[128:129]
	s_waitcnt vmcnt(0) lgkmcnt(0)
	s_barrier
	v_lshl_add_u64 v[0:1], s[64:65], 0, v[128:129]
	global_load_dwordx4 v[12:15], v[0:1], off
	global_load_dwordx4 v[8:11], v[0:1], off offset:64
	global_load_dwordx4 v[4:7], v[0:1], off offset:512
	s_nop 0
	global_load_dwordx4 v[0:3], v[0:1], off offset:576
	v_lshl_add_u32 v147, v146, 2, 0
	v_add_u32_e32 v149, 0x1000, v147
	ds_read2_b32 v[154:155], v149 offset1:16
	ds_read2_b32 v[158:159], v149 offset0:32 offset1:48
	v_add_u32_e32 v146, s10, v146
	v_add_u32_e32 v152, 32, v146
	v_ashrrev_i32_e32 v147, 31, v146
	v_add_u32_e32 v150, 16, v146
	v_ashrrev_i32_e32 v153, 31, v152
	v_lshlrev_b64 v[156:157], 13, v[146:147]
	v_ashrrev_i32_e32 v151, 31, v150
	v_lshlrev_b64 v[152:153], 13, v[152:153]
	v_lshl_add_u64 v[156:157], s[66:67], 0, v[156:157]
	v_lshlrev_b64 v[150:151], 13, v[150:151]
	v_lshl_add_u64 v[152:153], s[66:67], 0, v[152:153]
	s_waitcnt lgkmcnt(1)
	v_pk_mul_f32 v[124:125], v[124:125], v[154:155] op_sel_hi:[1,0]
	v_pk_mul_f32 v[126:127], v[126:127], v[154:155] op_sel_hi:[1,0]
	v_pk_mul_f32 v[120:121], v[120:121], v[154:155] op_sel_hi:[1,0]
	v_pk_mul_f32 v[122:123], v[122:123], v[154:155] op_sel_hi:[1,0]
	v_pk_mul_f32 v[116:117], v[116:117], v[154:155] op_sel_hi:[1,0]
	v_pk_mul_f32 v[118:119], v[118:119], v[154:155] op_sel_hi:[1,0]
	v_pk_mul_f32 v[112:113], v[112:113], v[154:155] op_sel_hi:[1,0]
	v_pk_mul_f32 v[114:115], v[114:115], v[154:155] op_sel_hi:[1,0]
	v_mov_b32_e32 v154, v155
	s_waitcnt lgkmcnt(0)
	v_pk_mul_f32 v[80:81], v[80:81], v[158:159] op_sel_hi:[1,0]
	v_pk_mul_f32 v[82:83], v[82:83], v[158:159] op_sel_hi:[1,0]
	v_lshl_add_u64 v[156:157], v[156:157], 0, v[128:129]
	v_lshl_add_u64 v[150:151], s[66:67], 0, v[150:151]
	v_lshl_add_u64 v[152:153], v[152:153], 0, v[128:129]
	v_pk_mul_f32 v[160:161], v[92:93], v[158:159] op_sel_hi:[1,0]
	v_pk_mul_f32 v[162:163], v[94:95], v[158:159] op_sel_hi:[1,0]
	v_pk_mul_f32 v[164:165], v[88:89], v[158:159] op_sel_hi:[1,0]
	v_pk_mul_f32 v[166:167], v[90:91], v[158:159] op_sel_hi:[1,0]
	v_pk_mul_f32 v[168:169], v[84:85], v[158:159] op_sel_hi:[1,0]
	v_pk_mul_f32 v[170:171], v[86:87], v[158:159] op_sel_hi:[1,0]
	v_pk_mul_f32 v[108:109], v[108:109], v[154:155] op_sel_hi:[1,0]
	v_pk_mul_f32 v[110:111], v[110:111], v[154:155] op_sel_hi:[1,0]
	v_pk_mul_f32 v[104:105], v[104:105], v[154:155] op_sel_hi:[1,0]
	v_pk_mul_f32 v[106:107], v[106:107], v[154:155] op_sel_hi:[1,0]
	v_pk_mul_f32 v[172:173], v[100:101], v[154:155] op_sel_hi:[1,0]
	v_pk_mul_f32 v[174:175], v[102:103], v[154:155] op_sel_hi:[1,0]
	v_pk_mul_f32 v[176:177], v[96:97], v[154:155] op_sel_hi:[1,0]
	v_pk_mul_f32 v[154:155], v[98:99], v[154:155] op_sel_hi:[1,0]
	v_lshl_add_u64 v[150:151], v[150:151], 0, v[128:129]
	s_waitcnt vmcnt(3)
	v_pk_mul_f32 v[86:87], v[14:15], v[126:127]
	v_pk_mul_f32 v[84:85], v[12:13], v[124:125]
	s_waitcnt vmcnt(2)
	v_pk_mul_f32 v[90:91], v[10:11], v[122:123]
	s_waitcnt vmcnt(0)
	v_pk_mul_f32 v[82:83], v[2:3], v[82:83]
	v_pk_mul_f32 v[80:81], v[0:1], v[80:81]
	v_pk_mul_f32 v[88:89], v[8:9], v[120:121]
	v_pk_mul_f32 v[94:95], v[6:7], v[118:119]
	v_pk_mul_f32 v[92:93], v[4:5], v[116:117]
	v_pk_mul_f32 v[98:99], v[2:3], v[114:115]
	v_pk_mul_f32 v[96:97], v[0:1], v[112:113]
	v_pk_mul_f32 v[102:103], v[14:15], v[110:111]
	v_pk_mul_f32 v[100:101], v[12:13], v[108:109]
	v_pk_mul_f32 v[106:107], v[10:11], v[106:107]
	v_pk_mul_f32 v[104:105], v[8:9], v[104:105]
	v_pk_mul_f32 v[110:111], v[6:7], v[174:175]
	v_pk_mul_f32 v[108:109], v[4:5], v[172:173]
	v_pk_mul_f32 v[114:115], v[2:3], v[154:155]
	v_pk_mul_f32 v[112:113], v[0:1], v[176:177]
	v_pk_mul_f32 v[118:119], v[14:15], v[162:163]
	v_pk_mul_f32 v[116:117], v[12:13], v[160:161]
	v_pk_mul_f32 v[122:123], v[10:11], v[166:167]
	v_pk_mul_f32 v[120:121], v[8:9], v[164:165]
	v_pk_mul_f32 v[126:127], v[6:7], v[170:171]
	v_pk_mul_f32 v[124:125], v[4:5], v[168:169]
	global_store_dwordx4 v[156:157], v[84:87], off nt
	global_store_dwordx4 v[156:157], v[88:91], off offset:64 nt
	global_store_dwordx4 v[156:157], v[92:95], off offset:512 nt
	global_store_dwordx4 v[156:157], v[96:99], off offset:576 nt
	global_store_dwordx4 v[150:151], v[100:103], off nt
	global_store_dwordx4 v[150:151], v[104:107], off offset:64 nt
	global_store_dwordx4 v[150:151], v[108:111], off offset:512 nt
	global_store_dwordx4 v[150:151], v[112:115], off offset:576 nt
	global_store_dwordx4 v[152:153], v[116:119], off nt
	global_store_dwordx4 v[152:153], v[120:123], off offset:64 nt
	global_store_dwordx4 v[152:153], v[124:127], off offset:512 nt
	global_store_dwordx4 v[152:153], v[80:83], off offset:576 nt
	s_nop 1
	v_add_u32_e32 v80, 48, v146
	v_ashrrev_i32_e32 v81, 31, v80
	v_lshlrev_b64 v[80:81], 13, v[80:81]
	v_mov_b32_e32 v82, v159
	v_lshl_add_u64 v[80:81], s[66:67], 0, v[80:81]
	v_pk_mul_f32 v[68:69], v[68:69], v[82:83] op_sel_hi:[1,0]
	v_pk_mul_f32 v[70:71], v[70:71], v[82:83] op_sel_hi:[1,0]
	v_lshl_add_u64 v[80:81], v[80:81], 0, v[128:129]
	v_pk_mul_f32 v[70:71], v[6:7], v[70:71]
	v_pk_mul_f32 v[68:69], v[4:5], v[68:69]
	global_store_dwordx4 v[80:81], v[68:71], off offset:512 nt
	v_pk_mul_f32 v[64:65], v[64:65], v[82:83] op_sel_hi:[1,0]
	v_pk_mul_f32 v[66:67], v[66:67], v[82:83] op_sel_hi:[1,0]
	ds_read2_b32 v[68:69], v149 offset0:128 offset1:144
	v_pk_mul_f32 v[66:67], v[2:3], v[66:67]
	v_pk_mul_f32 v[64:65], v[0:1], v[64:65]
	global_store_dwordx4 v[80:81], v[64:67], off offset:576 nt
	v_pk_mul_f32 v[76:77], v[76:77], v[82:83] op_sel_hi:[1,0]
	s_waitcnt lgkmcnt(0)
	v_pk_mul_f32 v[48:49], v[48:49], v[68:69] op_sel_hi:[1,0]
	v_add_u32_e32 v64, s10, v148
	v_ashrrev_i32_e32 v65, 31, v64
	v_lshlrev_b64 v[64:65], 13, v[64:65]
	v_lshl_add_u64 v[64:65], s[66:67], 0, v[64:65]
	v_pk_mul_f32 v[50:51], v[50:51], v[68:69] op_sel_hi:[1,0]
	v_lshl_add_u64 v[64:65], v[64:65], 0, v[128:129]
	v_pk_mul_f32 v[50:51], v[2:3], v[50:51]
	v_pk_mul_f32 v[48:49], v[0:1], v[48:49]
	global_store_dwordx4 v[64:65], v[48:51], off offset:576 nt
	v_pk_mul_f32 v[78:79], v[78:79], v[82:83] op_sel_hi:[1,0]
	v_pk_mul_f32 v[60:61], v[60:61], v[68:69] op_sel_hi:[1,0]
	v_add_u32_e32 v48, 0x90, v146
	v_ashrrev_i32_e32 v49, 31, v48
	v_lshlrev_b64 v[48:49], 13, v[48:49]
	v_mov_b32_e32 v50, v69
	v_lshl_add_u64 v[48:49], s[66:67], 0, v[48:49]
	v_pk_mul_f32 v[36:37], v[36:37], v[50:51] op_sel_hi:[1,0]
	v_pk_mul_f32 v[38:39], v[38:39], v[50:51] op_sel_hi:[1,0]
	v_lshl_add_u64 v[48:49], v[48:49], 0, v[128:129]
	v_pk_mul_f32 v[38:39], v[6:7], v[38:39]
	v_pk_mul_f32 v[36:37], v[4:5], v[36:37]
	global_store_dwordx4 v[48:49], v[36:39], off offset:512 nt
	v_pk_mul_f32 v[32:33], v[32:33], v[50:51] op_sel_hi:[1,0]
	v_pk_mul_f32 v[34:35], v[34:35], v[50:51] op_sel_hi:[1,0]
	ds_read2_b32 v[36:37], v149 offset0:160 offset1:176
	v_pk_mul_f32 v[34:35], v[2:3], v[34:35]
	v_pk_mul_f32 v[32:33], v[0:1], v[32:33]
	global_store_dwordx4 v[48:49], v[32:35], off offset:576 nt
	v_pk_mul_f32 v[62:63], v[62:63], v[68:69] op_sel_hi:[1,0]
	s_waitcnt lgkmcnt(0)
	v_pk_mul_f32 v[16:17], v[16:17], v[36:37] op_sel_hi:[1,0]
	v_add_u32_e32 v32, 0xa0, v146
	v_ashrrev_i32_e32 v33, 31, v32
	v_lshlrev_b64 v[32:33], 13, v[32:33]
	v_lshl_add_u64 v[32:33], s[66:67], 0, v[32:33]
	v_pk_mul_f32 v[18:19], v[18:19], v[36:37] op_sel_hi:[1,0]
	v_lshl_add_u64 v[32:33], v[32:33], 0, v[128:129]
	v_pk_mul_f32 v[18:19], v[2:3], v[18:19]
	v_pk_mul_f32 v[16:17], v[0:1], v[16:17]
	global_store_dwordx4 v[32:33], v[16:19], off offset:576 nt
	v_pk_mul_f32 v[20:21], v[20:21], v[36:37] op_sel_hi:[1,0]
	v_pk_mul_f32 v[22:23], v[22:23], v[36:37] op_sel_hi:[1,0]
	v_add_u32_e32 v16, 0xb0, v146
	v_ashrrev_i32_e32 v17, 31, v16
	v_pk_mul_f32 v[22:23], v[6:7], v[22:23]
	v_pk_mul_f32 v[20:21], v[4:5], v[20:21]
	v_lshlrev_b64 v[16:17], 13, v[16:17]
	v_mov_b32_e32 v18, v37
	v_pk_mul_f32 v[44:45], v[44:45], v[50:51] op_sel_hi:[1,0]
	v_pk_mul_f32 v[46:47], v[46:47], v[50:51] op_sel_hi:[1,0]
	v_pk_mul_f32 v[28:29], v[28:29], v[36:37] op_sel_hi:[1,0]
	v_pk_mul_f32 v[30:31], v[30:31], v[36:37] op_sel_hi:[1,0]
	global_store_dwordx4 v[32:33], v[20:23], off offset:512 nt
	v_lshl_add_u64 v[16:17], s[66:67], 0, v[16:17]
	v_pk_mul_f32 v[78:79], v[14:15], v[78:79]
	v_pk_mul_f32 v[20:21], v[144:145], v[18:19] op_sel_hi:[1,0]
	v_pk_mul_f32 v[22:23], v[142:143], v[18:19] op_sel_hi:[1,0]
	v_pk_mul_f32 v[76:77], v[12:13], v[76:77]
	v_pk_mul_f32 v[62:63], v[14:15], v[62:63]
	v_pk_mul_f32 v[60:61], v[12:13], v[60:61]
	v_pk_mul_f32 v[46:47], v[14:15], v[46:47]
	v_pk_mul_f32 v[44:45], v[12:13], v[44:45]
	v_pk_mul_f32 v[30:31], v[14:15], v[30:31]
	v_pk_mul_f32 v[28:29], v[12:13], v[28:29]
	v_pk_mul_f32 v[14:15], v[14:15], v[22:23]
	v_pk_mul_f32 v[12:13], v[12:13], v[20:21]
	v_lshl_add_u64 v[16:17], v[16:17], 0, v[128:129]
	global_store_dwordx4 v[80:81], v[76:79], off nt
	v_pk_mul_f32 v[72:73], v[72:73], v[82:83] op_sel_hi:[1,0]
	v_pk_mul_f32 v[74:75], v[74:75], v[82:83] op_sel_hi:[1,0]
	v_pk_mul_f32 v[56:57], v[56:57], v[68:69] op_sel_hi:[1,0]
	v_pk_mul_f32 v[58:59], v[58:59], v[68:69] op_sel_hi:[1,0]
	v_pk_mul_f32 v[40:41], v[40:41], v[50:51] op_sel_hi:[1,0]
	v_pk_mul_f32 v[42:43], v[42:43], v[50:51] op_sel_hi:[1,0]
	v_pk_mul_f32 v[24:25], v[24:25], v[36:37] op_sel_hi:[1,0]
	v_pk_mul_f32 v[26:27], v[26:27], v[36:37] op_sel_hi:[1,0]
	global_store_dwordx4 v[16:17], v[12:15], off nt
	v_pk_mul_f32 v[74:75], v[10:11], v[74:75]
	v_pk_mul_f32 v[72:73], v[8:9], v[72:73]
	v_pk_mul_f32 v[12:13], v[140:141], v[18:19] op_sel_hi:[1,0]
	v_pk_mul_f32 v[14:15], v[138:139], v[18:19] op_sel_hi:[1,0]
	v_pk_mul_f32 v[58:59], v[10:11], v[58:59]
	v_pk_mul_f32 v[56:57], v[8:9], v[56:57]
	v_pk_mul_f32 v[42:43], v[10:11], v[42:43]
	v_pk_mul_f32 v[40:41], v[8:9], v[40:41]
	v_pk_mul_f32 v[26:27], v[10:11], v[26:27]
	v_pk_mul_f32 v[24:25], v[8:9], v[24:25]
	v_pk_mul_f32 v[10:11], v[10:11], v[14:15]
	v_pk_mul_f32 v[8:9], v[8:9], v[12:13]
	global_store_dwordx4 v[80:81], v[72:75], off offset:64 nt
	v_pk_mul_f32 v[52:53], v[52:53], v[68:69] op_sel_hi:[1,0]
	v_pk_mul_f32 v[54:55], v[54:55], v[68:69] op_sel_hi:[1,0]
	global_store_dwordx4 v[16:17], v[8:11], off offset:64 nt
	v_pk_mul_f32 v[54:55], v[6:7], v[54:55]
	v_pk_mul_f32 v[52:53], v[4:5], v[52:53]
	v_pk_mul_f32 v[8:9], v[136:137], v[18:19] op_sel_hi:[1,0]
	v_pk_mul_f32 v[10:11], v[134:135], v[18:19] op_sel_hi:[1,0]
	v_pk_mul_f32 v[4:5], v[4:5], v[8:9]
	v_pk_mul_f32 v[6:7], v[6:7], v[10:11]
	global_store_dwordx4 v[16:17], v[4:7], off offset:512 nt
	global_store_dwordx4 v[64:65], v[60:63], off nt
	global_store_dwordx4 v[64:65], v[56:59], off offset:64 nt
	v_pk_mul_f32 v[4:5], v[132:133], v[18:19] op_sel_hi:[1,0]
	v_pk_mul_f32 v[6:7], v[130:131], v[18:19] op_sel_hi:[1,0]
	v_pk_mul_f32 v[0:1], v[0:1], v[4:5]
	v_pk_mul_f32 v[2:3], v[2:3], v[6:7]
	global_store_dwordx4 v[64:65], v[52:55], off offset:512 nt
	global_store_dwordx4 v[48:49], v[44:47], off nt
	global_store_dwordx4 v[48:49], v[40:43], off offset:64 nt
	global_store_dwordx4 v[32:33], v[28:31], off nt
	global_store_dwordx4 v[32:33], v[24:27], off offset:64 nt
	global_store_dwordx4 v[16:17], v[0:3], off offset:576 nt
